# v13 + phase-2 pre-work rebalanced: workgroups 0..63 take the 64 context-pass hyena filter units, 64..127 four weight tiles each, the upper half keeps the sample-pass filter units plus one weight tile
# speedup vs baseline: 1.0215x; 1.0033x over previous
.LBB0_217:
	s_or_b64 exec, exec, s[4:5]
	s_ashr_i32 s88, s56, 1
	s_cmp_ge_i32 s2, s88
	s_cselect_b64 s[4:5], -1, 0
	s_cmp_lt_i32 s2, s88
	v_writelane_b32 v254, s4, 0
	s_waitcnt lgkmcnt(0)
	s_barrier
	v_writelane_b32 v254, s5, 1
	s_cbranch_scc1 .Lp2_low
	s_load_dwordx2 s[4:5], s[0:1], 0x108
	s_sub_i32 s16, s2, s88
	s_movk_i32 s98, 0x140
	s_cmp_eq_u32 s56, 0x100
	s_cbranch_scc0 .Lp2_flt
	s_movk_i32 s98, 0x100
.Lp2_flt:
	s_cmp_ge_i32 s16, s98
	s_cbranch_scc1 .Lp2_flt_done
	s_load_dwordx2 s[6:7], s[0:1], 0xa0
	s_lshl_b32 s8, s2, 5
	s_lshl_b32 s9, s88, 5
	s_lshl_b32 s18, s16, 5
	s_lshl_b32 s8, s56, 5
	s_sub_i32 s17, s56, s88
	s_sub_i32 s19, s8, s9
	s_movk_i32 s20, 0x800
	s_mov_b32 s9, 0
	v_mov_b32_e32 v65, 0
	s_mov_b32 s21, 0xe85a000
	s_mov_b32 s22, 0xed9a000
	s_mov_b32 s23, 0xc47fc000
	v_mov_b32_e32 v68, 0xc0447cbd
	s_branch .LBB0_221
.LBB0_220:
	s_or_b64 exec, exec, s[10:11]
	s_add_i32 s16, s16, s17
	s_add_i32 s18, s18, s19
	s_cmp_lt_i32 s16, s98
	s_barrier
	s_cbranch_scc0 .Lp2_flt_done

.Lp2_low:
	s_cmp_eq_u32 s56, 0x100
	s_cbranch_scc0 .LBB0_232
	s_load_dwordx2 s[4:5], s[0:1], 0x108
	s_add_i32 s16, s2, 0x100
	s_movk_i32 s98, 0x140
	s_branch .Lp2_flt
.Lp2_flt_done:
	s_cmp_eq_u32 s56, 0x100
	s_cbranch_scc1 .Lp2_t256
	s_cmp_lt_i32 s2, s88
	s_cbranch_scc1 .LBB0_232
	s_sub_i32 s6, s2, s88
	s_sub_i32 s99, s56, s88
	s_movk_i32 s100, 0x300
	s_branch .LBB0_224
.Lp2_t256:
	s_cmp_lt_u32 s2, 64
	s_cbranch_scc1 .LBB0_232
	s_cmp_lt_u32 s2, 0x80
	s_cbranch_scc0 .Lp2_t_up
	s_sub_i32 s6, s2, 64
	s_movk_i32 s99, 64
	s_movk_i32 s100, 0x280
	s_branch .LBB0_224
.Lp2_t_up:
	s_add_i32 s6, s2, 0x80
	s_movk_i32 s99, 0x80
	s_movk_i32 s100, 0x300
.LBB0_224:
	s_add_i32 s12, s6, 0x180
	s_cmp_ge_i32 s12, s100
	s_cbranch_scc1 .LBB0_232
	s_load_dwordx2 s[6:7], s[0:1], 0x50
	s_lshl_b32 s8, s56, 6
	s_lshl_b32 s9, s88, 6
	s_lshl_b32 s14, s99, 6
	s_lshl_b32 s8, s56, 3
	s_lshl_b32 s9, s88, 3
	s_lshl_b32 s13, s12, 6
	s_lshl_b32 s15, s12, 3
	s_lshl_b32 s16, s99, 3
	v_mov_b32_e32 v1, 0
	s_mov_b32 s17, 0x9040
	s_movk_i32 s18, 0x204
	s_branch .LBB0_227
.LBB0_226:
	s_ashr_i32 s9, s8, 31
	s_and_b32 s10, s13, 0x3c0
	v_mov_b32_e32 v18, v234
	s_lshl_b64 s[8:9], s[8:9], 2
	s_waitcnt lgkmcnt(0)
	s_add_u32 s8, s6, s8
	v_lshlrev_b32_e32 v0, 4, v18
	s_addc_u32 s9, s7, s9
	v_and_b32_e32 v0, 0x1f0, v0
	v_ashrrev_i32_e32 v21, 5, v18
	v_lshl_add_u64 v[14:15], s[8:9], 0, v[0:1]
	v_add_u32_e32 v2, s10, v21
	v_mad_i64_i32 v[10:11], s[8:9], v2, s17, v[14:15]
	v_add_u32_e32 v2, 0x200, v18
	v_ashrrev_i32_e32 v23, 5, v2
	v_add_u32_e32 v2, s10, v23
	v_mad_i64_i32 v[12:13], s[8:9], v2, s17, v[14:15]
	global_load_dwordx4 v[2:5], v[10:11], off
	global_load_dwordx4 v[6:9], v[12:13], off
	v_add_u32_e32 v10, 0x400, v18
	v_ashrrev_i32_e32 v28, 5, v10
	v_add_u32_e32 v10, s10, v28
	v_add_u32_e32 v16, 0x600, v18
	v_mad_i64_i32 v[10:11], s[8:9], v10, s17, v[14:15]
	v_ashrrev_i32_e32 v30, 5, v16
	global_load_dwordx4 v[10:13], v[10:11], off
	v_add_u32_e32 v16, s10, v30
	v_mad_i64_i32 v[14:15], s[8:9], v16, s17, v[14:15]
	global_load_dwordx4 v[14:17], v[14:15], off
	v_ashrrev_i32_e32 v19, 3, v18
	v_lshlrev_b32_e32 v18, 3, v18
	v_and_b32_e32 v22, 56, v18
	v_add_u32_e32 v20, 0, v0
	s_lshl_b32 s8, s10, 1
	v_lshlrev_b32_e32 v31, 2, v19
	v_mul_u32_u24_e32 v32, 0x204, v22
	v_mad_u64_u32 v[24:25], s[10:11], v21, s18, v[20:21]
	v_mad_u64_u32 v[26:27], s[10:11], v23, s18, v[20:21]
	v_mad_u64_u32 v[28:29], s[10:11], v28, s18, v[20:21]
	v_mad_u64_u32 v[20:21], s[10:11], v30, s18, v[20:21]
	s_add_u32 s8, s4, s8
	v_add3_u32 v21, 0, v32, v31
	v_lshlrev_b32_e32 v0, 1, v22
	s_addc_u32 s9, s5, 0
	v_add_u32_e32 v25, 12, v21
	v_lshl_add_u64 v[30:31], s[8:9], 0, v[0:1]
	v_add_u32_e32 v0, 8, v21
	v_add_u32_e32 v27, 16, v21
	v_add_u32_e32 v29, 20, v21
	v_add_u32_e32 v32, 24, v21
	v_add_u32_e32 v33, 28, v21
	v_add_u32_e32 v18, s19, v19
	v_ashrrev_i32_e32 v19, 31, v18
	v_add_u32_e32 v22, 64, v18
	v_lshlrev_b64 v[18:19], 11, v[18:19]
	v_ashrrev_i32_e32 v23, 31, v22
	v_lshl_add_u64 v[18:19], v[30:31], 0, v[18:19]
	s_add_i32 s12, s12, s99
	s_nop 0
	s_add_i32 s13, s13, s14
	s_add_i32 s15, s15, s16
	s_cmp_lt_i32 s12, s100
	s_waitcnt vmcnt(3)
	ds_write2_b32 v24, v2, v3 offset1:1
	ds_write2_b32 v24, v4, v5 offset0:2 offset1:3
	s_waitcnt vmcnt(2)
	ds_write2_b32 v26, v6, v7 offset1:1
	ds_write2_b32 v26, v8, v9 offset0:2 offset1:3
	s_waitcnt vmcnt(1)
	ds_write2_b32 v28, v10, v11 offset1:1
	ds_write2_b32 v28, v12, v13 offset0:2 offset1:3
	s_waitcnt vmcnt(0)
	ds_write2_b32 v20, v14, v15 offset1:1
	ds_write2_b32 v20, v16, v17 offset0:2 offset1:3
	s_waitcnt lgkmcnt(0)
	s_barrier
	ds_read2st64_b32 v[6:7], v21 offset1:1
	ds_read2_b32 v[8:9], v21 offset0:129 offset1:193
	ds_read2st64_b32 v[10:11], v0 offset0:4 offset1:5
	ds_read2st64_b32 v[12:13], v25 offset0:6 offset1:7
	ds_read2st64_b32 v[14:15], v27 offset0:8 offset1:9
	ds_read2st64_b32 v[16:17], v29 offset0:10 offset1:11
	ds_read2st64_b32 v[20:21], v32 offset0:12 offset1:13
	ds_read2st64_b32 v[24:25], v33 offset0:14 offset1:15
	s_waitcnt lgkmcnt(6)
	v_cvt_pk_bf16_f32 v2, v6, v8
	s_waitcnt lgkmcnt(4)
	v_cvt_pk_bf16_f32 v3, v10, v12
	s_waitcnt lgkmcnt(2)
	v_cvt_pk_bf16_f32 v4, v14, v16
	v_cvt_pk_bf16_f32 v6, v7, v9
	s_waitcnt lgkmcnt(0)
	v_cvt_pk_bf16_f32 v5, v20, v24
	global_store_dwordx4 v[18:19], v[2:5], off
	v_cvt_pk_bf16_f32 v7, v11, v13
	v_cvt_pk_bf16_f32 v8, v15, v17
	v_lshlrev_b64 v[2:3], 11, v[22:23]
	v_cvt_pk_bf16_f32 v9, v21, v25
	v_lshl_add_u64 v[2:3], v[30:31], 0, v[2:3]
	global_store_dwordx4 v[2:3], v[6:9], off
	s_barrier
	s_cbranch_scc0 .LBB0_232
